# GQA loop: K-tile LDS writes hoisted ahead of the post-PV barrier so the second per-tile barrier and its lgkmcnt drain are removed (one barrier per key tile)
# speedup vs baseline: 1.0315x; 1.0105x over previous
; #define SBAR() __builtin_amdgcn_sched_barrier(0)
; #define SLOAD(i, k0) do { sr_[i].vs0 = *reinterpret_cast<const bf16x8*>(vptr + (size_t)((k0) + sr) * vstr); \
;     sr_[i].vs1 = *reinterpret_cast<const bf16x8*>(vptr + (size_t)((k0) + 32 + sr) * vstr); \
;     sr_[i].ks0 = *reinterpret_cast<const bf16x8*>(kptr + (size_t)((k0) + sr) * kstr); \
;     sr_[i].ks1 = *reinterpret_cast<const bf16x8*>(kptr + (size_t)((k0) + 32 + sr) * kstr); } while (0)
; #define SWRITE(b, i) do { *(LAS bf16x8*)(V_lds + (b) * SHM_V + vst0) = sr_[i].vs0;          \
;     *(LAS bf16x8*)(V_lds + (b) * SHM_V + vst1) = sr_[i].vs1; const int kc = sc * 2;               \
;     *(LAS bf16x8*)(K_lds + (b) * SHM_K + KSWZ(sr, kc)) = sr_[i].ks0;                       \
;     *(LAS bf16x8*)(K_lds + (b) * SHM_K + KSWZ(32 + sr, kc)) = sr_[i].ks1; } while (0)
; #define SWAIT() asm volatile("s_waitcnt vmcnt(4)" ::: "memory")
; template <int NDQ, int NDV> ...
;     ...
;     SBAR(); qkt<NDQ>(pB0, pB1, K_lds + SHM_K, qr, r32, hi);
;     finishSM(pA0, pA1, alA, l_reg, pa0, pa1, pa2, pa3); SBAR();
;     SLOAD(SO, (j + 2) * 64); SBAR();
;     pv_d0<NDV>(o, vb0, pa0, pa1, pa2, pa3); partialSM(pB0, pB1, m_reg, mnB, alB, Cs, thr);
;     ...
;     __syncthreads(); SWAIT(); SWRITE(1, SO);
.LBB0_2123:
	ds_read_b128 v[64:67], v199 offset:49152
	ds_read_b128 v[68:71], v199 offset:57344
	ds_read_b128 v[216:219], v200 offset:49152
	ds_read_b128 v[220:223], v200 offset:57344
	v_add_f32_e32 v161, 0, v236
	v_add_f32_e32 v161, v237, v161
	s_waitcnt lgkmcnt(3)
	v_mfma_f32_32x32x16_bf16 v[80:95], v[64:67], v[124:127], 0
	v_add_f32_e32 v161, v238, v161
	v_add_f32_e32 v161, v239, v161
	v_add_f32_e32 v161, v240, v161
	v_add_f32_e32 v161, v241, v161
	v_add_f32_e32 v161, v242, v161
	v_add_f32_e32 v161, v243, v161
	s_waitcnt lgkmcnt(2)
	v_mfma_f32_32x32x16_bf16 v[64:79], v[68:71], v[124:127], 0
	v_add_f32_e32 v161, v244, v161
	v_add_f32_e32 v161, v245, v161
	v_add_f32_e32 v161, v246, v161
	v_add_f32_e32 v161, v247, v161
	v_exp_f32_e32 v154, v154
	s_waitcnt lgkmcnt(1)
	v_mfma_f32_32x32x16_bf16 v[80:95], v[216:219], v[120:123], v[80:95]
	v_add_f32_e32 v161, v248, v161
	v_exp_f32_e32 v155, v155
	v_add_f32_e32 v161, v249, v161
	v_exp_f32_e32 v152, v152
	s_waitcnt lgkmcnt(0)
	v_mfma_f32_32x32x16_bf16 v[64:79], v[220:223], v[120:123], v[64:79]
	ds_read_b128 v[216:219], v201 offset:49152
	ds_read_b128 v[220:223], v201 offset:57344
	v_add_f32_e32 v161, v250, v161
	v_exp_f32_e32 v153, v153
	v_add_f32_e32 v161, v251, v161
	v_exp_f32_e32 v148, v148
	s_waitcnt lgkmcnt(1)
	v_mfma_f32_32x32x16_bf16 v[80:95], v[216:219], v[116:119], v[80:95]
	v_add_f32_e32 v161, v154, v161
	v_exp_f32_e32 v149, v149
	v_add_f32_e32 v161, v155, v161
	v_exp_f32_e32 v146, v146
	s_waitcnt lgkmcnt(0)
	v_mfma_f32_32x32x16_bf16 v[64:79], v[220:223], v[116:119], v[64:79]
	ds_read_b128 v[216:219], v202 offset:49152
	ds_read_b128 v[220:223], v202 offset:57344
	v_add_f32_e32 v161, v152, v161
	v_exp_f32_e32 v147, v147
	v_add_f32_e32 v161, v153, v161
	v_exp_f32_e32 v144, v144
	s_waitcnt lgkmcnt(1)
	v_mfma_f32_32x32x16_bf16 v[80:95], v[216:219], v[112:115], v[80:95]
	v_add_f32_e32 v161, v148, v161
	v_exp_f32_e32 v145, v145
	v_add_f32_e32 v161, v149, v161
	v_exp_f32_e32 v158, v158
	s_waitcnt lgkmcnt(0)
	v_mfma_f32_32x32x16_bf16 v[64:79], v[220:223], v[112:115], v[64:79]
	ds_read_b128 v[216:219], v203 offset:49152
	ds_read_b128 v[220:223], v203 offset:57344
	v_add_f32_e32 v161, v146, v161
	v_exp_f32_e32 v159, v159
	v_add_f32_e32 v161, v147, v161
	v_exp_f32_e32 v156, v156
	s_waitcnt lgkmcnt(1)
	v_mfma_f32_32x32x16_bf16 v[80:95], v[216:219], v[108:111], v[80:95]
	v_add_f32_e32 v161, v144, v161
	v_exp_f32_e32 v157, v157
	v_add_f32_e32 v161, v145, v161
	v_exp_f32_e32 v150, v150
	s_waitcnt lgkmcnt(0)
	v_mfma_f32_32x32x16_bf16 v[64:79], v[220:223], v[108:111], v[64:79]
	ds_read_b128 v[216:219], v204 offset:49152
	ds_read_b128 v[220:223], v204 offset:57344
	v_add_f32_e32 v161, v158, v161
	v_exp_f32_e32 v151, v151
	v_add_f32_e32 v161, v159, v161
	v_add_f32_e32 v161, v156, v161
	v_add_f32_e32 v161, v157, v161
	s_waitcnt lgkmcnt(1)
	v_mfma_f32_32x32x16_bf16 v[80:95], v[216:219], v[104:107], v[80:95]
	v_add_f32_e32 v161, v150, v161
	v_add_f32_e32 v208, v151, v161
	v_mov_b32_e32 v209, v208
	v_cvt_pk_bf16_f32 v210, v236, v237
	v_cvt_pk_bf16_f32 v211, v238, v239
	v_cvt_pk_bf16_f32 v212, v240, v241
	s_waitcnt lgkmcnt(0)
	v_mfma_f32_32x32x16_bf16 v[64:79], v[220:223], v[104:107], v[64:79]
	ds_read_b128 v[216:219], v205 offset:49152
	ds_read_b128 v[220:223], v205 offset:57344
	v_permlane32_swap_b32_e32 v208, v209
	v_cvt_pk_bf16_f32 v213, v242, v243
	v_cvt_pk_bf16_f32 v170, v244, v245
	v_cvt_pk_bf16_f32 v171, v246, v247
	v_permlane32_swap_b32_e32 v210, v212
	v_cvt_pk_bf16_f32 v172, v248, v249
	s_waitcnt lgkmcnt(1)
	v_mfma_f32_32x32x16_bf16 v[80:95], v[216:219], v[100:103], v[80:95]
	v_cvt_pk_bf16_f32 v173, v250, v251
	v_cvt_pk_bf16_f32 v162, v154, v155
	v_cvt_pk_bf16_f32 v163, v152, v153
	v_cvt_pk_bf16_f32 v164, v148, v149
	v_cvt_pk_bf16_f32 v165, v146, v147
	v_cvt_pk_bf16_f32 v166, v144, v145
	s_waitcnt lgkmcnt(0)
	v_mfma_f32_32x32x16_bf16 v[64:79], v[220:223], v[100:103], v[64:79]
	ds_read_b128 v[216:219], v206 offset:49152
	ds_read_b128 v[220:223], v206 offset:57344
	v_cvt_pk_bf16_f32 v167, v158, v159
	v_cvt_pk_bf16_f32 v168, v156, v157
	v_cvt_pk_bf16_f32 v169, v150, v151
	v_permlane32_swap_b32_e32 v211, v213
	v_permlane32_swap_b32_e32 v170, v172
	v_permlane32_swap_b32_e32 v171, v173
	s_waitcnt lgkmcnt(1)
	v_mfma_f32_32x32x16_bf16 v[80:95], v[216:219], v[96:99], v[80:95]
	v_permlane32_swap_b32_e32 v162, v164
	v_permlane32_swap_b32_e32 v163, v165
	v_permlane32_swap_b32_e32 v166, v168
	v_permlane32_swap_b32_e32 v167, v169
	s_waitcnt lgkmcnt(0)
	v_mfma_f32_32x32x16_bf16 v[64:79], v[220:223], v[96:99], v[64:79]
	v_add_co_u32_e32 v148, vcc, s50, v184
	s_nop 1
	v_addc_co_u32_e32 v149, vcc, -1, v185, vcc
	v_add_co_u32_e32 v152, vcc, s51, v184
	s_nop 1
	v_addc_co_u32_e32 v153, vcc, -1, v185, vcc
	global_load_dwordx4 v[144:147], v[148:149], off
	s_nop 0
	global_load_dwordx4 v[148:151], v[148:149], off offset:-512
	s_nop 0
	global_load_dwordx4 v[156:159], v[152:153], off
	s_nop 0
	global_load_dwordx4 v[152:155], v[152:153], off offset:-512
	s_waitcnt vmcnt(4)
	ds_write_b128 v195, v[140:143] offset:32768
	ds_write_b128 v196, v[132:135] offset:32768
	ds_read_b64_tr_b16 v[214:215], v194 offset:0
	ds_read_b64_tr_b16 v[216:217], v194 offset:0x800
	ds_read_b64_tr_b16 v[218:219], v194 offset:0x1000
	ds_read_b64_tr_b16 v[220:221], v194 offset:0x1800
	ds_read_b64_tr_b16 v[222:223], v194 offset:0x2000
	ds_read_b64_tr_b16 v[224:225], v194 offset:0x2800
	ds_read_b64_tr_b16 v[226:227], v194 offset:0x3000
	ds_read_b64_tr_b16 v[228:229], v194 offset:0x3800
	s_waitcnt lgkmcnt(6)
; #define SWRITE(b, i) do { *(LAS bf16x8*)(V_lds + (b) * SHM_V + vst0) = sr_[i].vs0;          \
;     *(LAS bf16x8*)(V_lds + (b) * SHM_V + vst1) = sr_[i].vs1; const int kc = sc * 2;               \
;     *(LAS bf16x8*)(K_lds + (b) * SHM_K + KSWZ(sr, kc)) = sr_[i].ks0;                       \
;     *(LAS bf16x8*)(K_lds + (b) * SHM_K + KSWZ(32 + sr, kc)) = sr_[i].ks1; } while (0)
; #define SWAIT() asm volatile("s_waitcnt vmcnt(4)" ::: "memory")
; #define RESC(a) do { if (__any((a) < 1.f)) { if (hi == 0) al_l[r32] = (a); asm volatile("s_waitcnt lgkmcnt(0)" ::: "memory"); \
;     _Pragma("unroll") for (int d = 0; d < NDV; ++d) _Pragma("unroll") for (int r = 0; r < 16; ++r) o[d][r] *= al_l[crow(r, hi)]; } } while (0)
; template <int NDQ, int NDV> ...
;     ...
;     pv_d0<NDV>(o, vb0, pa0, pa1, pa2, pa3); partialSM(pB0, pB1, m_reg, mnB, alB, Cs, thr);
;     __syncthreads(); SWAIT(); SWRITE(0, SE);
;     RESC(alB); __syncthreads();
	v_mfma_f32_32x32x16_bf16 v[0:15], v[210:213], v[214:217], v[0:15]
	ds_read_b64_tr_b16 v[214:215], v194 offset:0x200
	ds_read_b64_tr_b16 v[216:217], v194 offset:0xa00
	v_max_f32_e32 v161, v81, v81
	v_max_f32_e32 v174, v80, v80
	v_max_f32_e32 v161, v174, v161
	v_max3_f32 v161, v161, v82, v83
	v_max3_f32 v161, v161, v84, v85
	v_max3_f32 v161, v161, v86, v87
	s_waitcnt lgkmcnt(6)
	v_mfma_f32_32x32x16_bf16 v[0:15], v[170:173], v[218:221], v[0:15]
	ds_read_b64_tr_b16 v[218:219], v194 offset:0x1200
	ds_read_b64_tr_b16 v[220:221], v194 offset:0x1a00
	v_max3_f32 v161, v161, v88, v89
	v_max3_f32 v161, v161, v90, v91
	v_max3_f32 v161, v161, v92, v93
	v_max3_f32 v161, v161, v94, v95
	v_max3_f32 v161, v161, v64, v65
	v_max3_f32 v161, v161, v66, v67
	s_waitcnt lgkmcnt(6)
	v_mfma_f32_32x32x16_bf16 v[0:15], v[162:165], v[222:225], v[0:15]
	ds_read_b64_tr_b16 v[222:223], v194 offset:0x2200
	ds_read_b64_tr_b16 v[224:225], v194 offset:0x2a00
	ds_read_b64_tr_b16 v[230:231], v194 offset:0x3200
	ds_read_b64_tr_b16 v[232:233], v194 offset:0x3a00
	v_max3_f32 v161, v161, v68, v69
	v_max3_f32 v161, v161, v70, v71
	v_max3_f32 v161, v161, v72, v73
	v_max3_f32 v161, v161, v74, v75
	v_max3_f32 v161, v161, v76, v77
	v_max3_f32 v161, v161, v78, v79
	s_waitcnt lgkmcnt(8)
	v_mfma_f32_32x32x16_bf16 v[0:15], v[166:169], v[226:229], v[0:15]
	v_mov_b32_e32 v174, v161
	s_nop 1
	v_permlane32_swap_b32_e32 v161, v174
	v_max_f32_e32 v175, v174, v174
	v_max_f32_e32 v161, v161, v161
	v_max_f32_e32 v161, v161, v175
	s_waitcnt lgkmcnt(6)
	v_mfma_f32_32x32x16_bf16 v[48:63], v[210:213], v[214:217], v[48:63]
	ds_read_b64_tr_b16 v[214:215], v194 offset:0x400
	ds_read_b64_tr_b16 v[216:217], v194 offset:0xc00
	v_max_f32_e32 v235, v160, v160
	v_sub_f32_e32 v175, v161, v160
	v_max_f32_e32 v161, v235, v161
	v_sub_f32_e32 v235, v160, v161
	v_mul_f32_e32 v235, 0x3e0293ee, v235
	s_waitcnt lgkmcnt(6)
	v_mfma_f32_32x32x16_bf16 v[48:63], v[170:173], v[218:221], v[48:63]
	ds_read_b64_tr_b16 v[218:219], v194 offset:0x1400
	ds_read_b64_tr_b16 v[220:221], v194 offset:0x1c00
	v_exp_f32_e32 v235, v235
	v_cmp_ge_f32_e32 vcc, s48, v175
	s_cmp_eq_u64 vcc, exec
	s_cselect_b64 s[2:3], -1, 0
	v_cndmask_b32_e64 v234, v161, v160, s[2:3]
	s_waitcnt lgkmcnt(6)
	v_mfma_f32_32x32x16_bf16 v[48:63], v[162:165], v[222:225], v[48:63]
	ds_read_b64_tr_b16 v[222:223], v194 offset:0x2400
	ds_read_b64_tr_b16 v[224:225], v194 offset:0x2c00
	ds_read_b64_tr_b16 v[226:227], v194 offset:0x3400
	ds_read_b64_tr_b16 v[228:229], v194 offset:0x3c00
	v_mul_f32_e32 v175, 0xbe0293ee, v234
	v_fmamk_f32 v80, v80, 0x3e0293ee, v175
	v_fmamk_f32 v81, v81, 0x3e0293ee, v175
	v_fmamk_f32 v82, v82, 0x3e0293ee, v175
	v_fmamk_f32 v83, v83, 0x3e0293ee, v175
	v_fmamk_f32 v84, v84, 0x3e0293ee, v175
	s_waitcnt lgkmcnt(8)
	v_mfma_f32_32x32x16_bf16 v[48:63], v[166:169], v[230:233], v[48:63]
	v_fmamk_f32 v85, v85, 0x3e0293ee, v175
	v_fmamk_f32 v86, v86, 0x3e0293ee, v175
	v_fmamk_f32 v87, v87, 0x3e0293ee, v175
	v_fmamk_f32 v88, v88, 0x3e0293ee, v175
	v_fmamk_f32 v89, v89, 0x3e0293ee, v175
	v_fmamk_f32 v90, v90, 0x3e0293ee, v175
	s_waitcnt lgkmcnt(6)
	v_mfma_f32_32x32x16_bf16 v[32:47], v[210:213], v[214:217], v[32:47]
	ds_read_b64_tr_b16 v[214:215], v194 offset:0x600
	ds_read_b64_tr_b16 v[216:217], v194 offset:0xe00
	v_fmamk_f32 v91, v91, 0x3e0293ee, v175
	v_fmamk_f32 v92, v92, 0x3e0293ee, v175
	v_fmamk_f32 v93, v93, 0x3e0293ee, v175
	v_fmamk_f32 v94, v94, 0x3e0293ee, v175
	v_fmamk_f32 v95, v95, 0x3e0293ee, v175
	s_waitcnt lgkmcnt(6)
	v_mfma_f32_32x32x16_bf16 v[32:47], v[170:173], v[218:221], v[32:47]
	ds_read_b64_tr_b16 v[218:219], v194 offset:0x1600
	ds_read_b64_tr_b16 v[220:221], v194 offset:0x1e00
	v_exp_f32_e32 v236, v80
	v_exp_f32_e32 v237, v81
	v_exp_f32_e32 v238, v82
	s_waitcnt lgkmcnt(6)
	v_mfma_f32_32x32x16_bf16 v[32:47], v[162:165], v[222:225], v[32:47]
	ds_read_b64_tr_b16 v[222:223], v194 offset:0x2600
	ds_read_b64_tr_b16 v[224:225], v194 offset:0x2e00
	ds_read_b64_tr_b16 v[230:231], v194 offset:0x3600
	ds_read_b64_tr_b16 v[232:233], v194 offset:0x3e00
	v_exp_f32_e32 v239, v83
	v_exp_f32_e32 v240, v84
	v_exp_f32_e32 v241, v85
	s_waitcnt lgkmcnt(8)
	v_mfma_f32_32x32x16_bf16 v[32:47], v[166:169], v[226:229], v[32:47]
	v_exp_f32_e32 v242, v86
	v_exp_f32_e32 v243, v87
	v_exp_f32_e32 v244, v88
	s_waitcnt lgkmcnt(6)
	v_mfma_f32_32x32x16_bf16 v[16:31], v[210:213], v[214:217], v[16:31]
	v_exp_f32_e32 v245, v89
	v_exp_f32_e32 v246, v90
	v_exp_f32_e32 v247, v91
	s_waitcnt lgkmcnt(4)
	v_mfma_f32_32x32x16_bf16 v[16:31], v[170:173], v[218:221], v[16:31]
	v_exp_f32_e32 v248, v92
	v_exp_f32_e32 v249, v93
	v_exp_f32_e32 v250, v94
	s_waitcnt lgkmcnt(2)
	v_mfma_f32_32x32x16_bf16 v[16:31], v[162:165], v[222:225], v[16:31]
	v_exp_f32_e32 v251, v95
	s_waitcnt lgkmcnt(0)
	v_mfma_f32_32x32x16_bf16 v[16:31], v[166:169], v[230:233], v[16:31]
	s_barrier
	s_waitcnt vmcnt(4)
	v_cndmask_b32_e64 v210, v235, 1.0, s[2:3]
	v_cmp_gt_f32_e32 vcc, 1.0, v210
	s_waitcnt vmcnt(4)
	ds_write_b128 v197, v[128:131]
	ds_write_b128 v198, v[136:139]
	s_cbranch_vccz .LBB0_2127
	s_and_saveexec_b64 s[30:31], s[0:1]
	ds_write_b32 v191, v210 offset:128
	s_or_b64 exec, exec, s[30:31]
	s_waitcnt lgkmcnt(0)
	v_add_u32_e32 v174, v183, v176
	ds_read_b128 v[162:165], v174 offset:224
	ds_read_b128 v[166:169], v174 offset:192
	ds_read_b128 v[170:173], v174 offset:160
	ds_read_b128 v[212:215], v174 offset:128
	s_waitcnt lgkmcnt(3)
	v_pk_mul_f32 v[12:13], v[12:13], v[162:163]
	s_waitcnt lgkmcnt(2)
	v_pk_mul_f32 v[8:9], v[8:9], v[166:167]
	s_waitcnt lgkmcnt(1)
	v_pk_mul_f32 v[4:5], v[4:5], v[170:171]
	v_pk_mul_f32 v[14:15], v[14:15], v[164:165]
	v_pk_mul_f32 v[10:11], v[10:11], v[168:169]
	v_pk_mul_f32 v[6:7], v[6:7], v[172:173]
	s_waitcnt lgkmcnt(0)
	v_pk_mul_f32 v[2:3], v[2:3], v[214:215]
	v_pk_mul_f32 v[0:1], v[0:1], v[212:213]
	v_pk_mul_f32 v[60:61], v[60:61], v[162:163]
	v_pk_mul_f32 v[56:57], v[56:57], v[166:167]
	v_pk_mul_f32 v[52:53], v[52:53], v[170:171]
	v_pk_mul_f32 v[62:63], v[62:63], v[164:165]
	v_pk_mul_f32 v[58:59], v[58:59], v[168:169]
	v_pk_mul_f32 v[54:55], v[54:55], v[172:173]
	v_pk_mul_f32 v[50:51], v[50:51], v[214:215]
	v_pk_mul_f32 v[48:49], v[48:49], v[212:213]
	v_pk_mul_f32 v[44:45], v[44:45], v[162:163]
	v_pk_mul_f32 v[40:41], v[40:41], v[166:167]
	v_pk_mul_f32 v[36:37], v[36:37], v[170:171]
	v_pk_mul_f32 v[46:47], v[46:47], v[164:165]
	v_pk_mul_f32 v[42:43], v[42:43], v[168:169]
	v_pk_mul_f32 v[38:39], v[38:39], v[172:173]
	v_pk_mul_f32 v[34:35], v[34:35], v[214:215]
	v_pk_mul_f32 v[32:33], v[32:33], v[212:213]
	v_pk_mul_f32 v[28:29], v[28:29], v[162:163]
	v_pk_mul_f32 v[24:25], v[24:25], v[166:167]
	v_pk_mul_f32 v[20:21], v[20:21], v[170:171]
	v_pk_mul_f32 v[30:31], v[30:31], v[164:165]
	v_pk_mul_f32 v[26:27], v[26:27], v[168:169]
	v_pk_mul_f32 v[22:23], v[22:23], v[172:173]
	v_pk_mul_f32 v[18:19], v[18:19], v[214:215]
	v_pk_mul_f32 v[16:17], v[16:17], v[212:213]
; #define SBAR() __builtin_amdgcn_sched_barrier(0)
; #define SLOAD(i, k0) do { sr_[i].vs0 = *reinterpret_cast<const bf16x8*>(vptr + (size_t)((k0) + sr) * vstr); \
;     sr_[i].vs1 = *reinterpret_cast<const bf16x8*>(vptr + (size_t)((k0) + 32 + sr) * vstr); \
;     sr_[i].ks0 = *reinterpret_cast<const bf16x8*>(kptr + (size_t)((k0) + sr) * kstr); \
;     sr_[i].ks1 = *reinterpret_cast<const bf16x8*>(kptr + (size_t)((k0) + 32 + sr) * kstr); } while (0)
; #define RESC(a) do { if (__any((a) < 1.f)) { if (hi == 0) al_l[r32] = (a); asm volatile("s_waitcnt lgkmcnt(0)" ::: "memory"); \
;     _Pragma("unroll") for (int d = 0; d < NDV; ++d) _Pragma("unroll") for (int r = 0; r < 16; ++r) o[d][r] *= al_l[crow(r, hi)]; } } while (0)
; template <int NDQ, int NDV> ...
;     ...
;     RESC(alB); __syncthreads();
;     SBAR(); qkt<NDQ>(pA0, pA1, K_lds, qr, r32, hi);
;     finishSM(pB0, pB1, alB, l_reg, pa0, pa1, pa2, pa3); SBAR();
;     if (j + 3 < NT) SLOAD(SE, (j + 3) * 64); SBAR();
.LBB0_2127:
	v_mov_b32_e32 v211, v234
	v_fmamk_f32 v221, v64, 0x3e0293ee, v175
	v_fmamk_f32 v222, v65, 0x3e0293ee, v175
	v_fmamk_f32 v223, v66, 0x3e0293ee, v175
	v_fmamk_f32 v224, v67, 0x3e0293ee, v175
	v_fmamk_f32 v225, v68, 0x3e0293ee, v175
	v_fmamk_f32 v214, v69, 0x3e0293ee, v175
	v_fmamk_f32 v215, v70, 0x3e0293ee, v175
	v_fmamk_f32 v216, v71, 0x3e0293ee, v175
	v_fmamk_f32 v217, v72, 0x3e0293ee, v175
	v_fmamk_f32 v218, v73, 0x3e0293ee, v175
	v_fmamk_f32 v219, v74, 0x3e0293ee, v175
	v_fmamk_f32 v220, v75, 0x3e0293ee, v175
	v_fmamk_f32 v213, v76, 0x3e0293ee, v175
	v_fmamk_f32 v226, v77, 0x3e0293ee, v175
	v_fmamk_f32 v227, v78, 0x3e0293ee, v175
	v_fmamk_f32 v212, v79, 0x3e0293ee, v175
	s_add_i32 s61, s61, 2
	ds_read_b128 v[64:67], v199 offset:32768
	ds_read_b128 v[68:71], v199 offset:40960
	ds_read_b128 v[228:231], v200 offset:32768
	ds_read_b128 v[232:235], v200 offset:40960
	v_exp_f32_e32 v221, v221
	s_waitcnt lgkmcnt(3)
	v_mfma_f32_32x32x16_bf16 v[80:95], v[64:67], v[124:127], 0
	v_exp_f32_e32 v222, v222
	v_exp_f32_e32 v223, v223
	v_exp_f32_e32 v224, v224
	s_waitcnt lgkmcnt(2)
	v_mfma_f32_32x32x16_bf16 v[64:79], v[68:71], v[124:127], 0
	v_exp_f32_e32 v225, v225
	v_exp_f32_e32 v214, v214
	v_exp_f32_e32 v215, v215
	s_waitcnt lgkmcnt(1)
	v_mfma_f32_32x32x16_bf16 v[80:95], v[228:231], v[120:123], v[80:95]
	v_exp_f32_e32 v216, v216
	v_exp_f32_e32 v217, v217
	v_exp_f32_e32 v218, v218
	s_waitcnt lgkmcnt(0)
	v_mfma_f32_32x32x16_bf16 v[64:79], v[232:235], v[120:123], v[64:79]
	ds_read_b128 v[228:231], v201 offset:32768
	ds_read_b128 v[232:235], v201 offset:40960
	v_exp_f32_e32 v219, v219
	v_exp_f32_e32 v220, v220
	v_exp_f32_e32 v226, v226
	s_waitcnt lgkmcnt(1)
	v_mfma_f32_32x32x16_bf16 v[80:95], v[228:231], v[116:119], v[80:95]
	v_exp_f32_e32 v227, v227
	v_exp_f32_e32 v253, v212
	v_exp_f32_e32 v252, v213
	s_waitcnt lgkmcnt(0)
	v_mfma_f32_32x32x16_bf16 v[64:79], v[232:235], v[116:119], v[64:79]
	ds_read_b128 v[228:231], v202 offset:32768
	ds_read_b128 v[232:235], v202 offset:40960
	v_add_f32_e32 v212, 0, v236
	v_add_f32_e32 v212, v237, v212
	v_add_f32_e32 v212, v238, v212
	v_add_f32_e32 v212, v239, v212
	v_add_f32_e32 v212, v240, v212
	v_add_f32_e32 v212, v241, v212
	s_waitcnt lgkmcnt(1)
	v_mfma_f32_32x32x16_bf16 v[80:95], v[228:231], v[112:115], v[80:95]
	v_add_f32_e32 v212, v242, v212
	v_add_f32_e32 v212, v243, v212
	v_add_f32_e32 v212, v244, v212
	v_add_f32_e32 v212, v245, v212
	v_add_f32_e32 v212, v246, v212
	v_add_f32_e32 v212, v247, v212
	s_waitcnt lgkmcnt(0)
	v_mfma_f32_32x32x16_bf16 v[64:79], v[232:235], v[112:115], v[64:79]
	ds_read_b128 v[228:231], v203 offset:32768
	ds_read_b128 v[232:235], v203 offset:40960
	v_add_f32_e32 v212, v248, v212
	v_add_f32_e32 v212, v249, v212
	v_add_f32_e32 v212, v250, v212
	v_add_f32_e32 v212, v251, v212
	v_add_f32_e32 v212, v221, v212
	v_add_f32_e32 v212, v222, v212
	s_waitcnt lgkmcnt(1)
	v_mfma_f32_32x32x16_bf16 v[80:95], v[228:231], v[108:111], v[80:95]
	v_add_f32_e32 v212, v223, v212
	v_add_f32_e32 v212, v224, v212
	v_add_f32_e32 v212, v225, v212
	v_add_f32_e32 v212, v214, v212
	v_add_f32_e32 v212, v215, v212
	v_add_f32_e32 v212, v216, v212
	s_waitcnt lgkmcnt(0)
	v_mfma_f32_32x32x16_bf16 v[64:79], v[232:235], v[108:111], v[64:79]
	ds_read_b128 v[228:231], v204 offset:32768
	ds_read_b128 v[232:235], v204 offset:40960
	v_add_f32_e32 v212, v217, v212
	v_add_f32_e32 v212, v218, v212
	v_add_f32_e32 v212, v219, v212
	v_add_f32_e32 v212, v220, v212
	v_add_f32_e32 v212, v252, v212
	v_add_f32_e32 v212, v226, v212
	s_waitcnt lgkmcnt(1)
	v_mfma_f32_32x32x16_bf16 v[80:95], v[228:231], v[104:107], v[80:95]
	v_add_f32_e32 v212, v227, v212
	v_add_f32_e32 v212, v253, v212
	v_mov_b32_e32 v213, v212
	v_cvt_pk_bf16_f32 v160, v236, v237
	v_cvt_pk_bf16_f32 v161, v238, v239
	v_cvt_pk_bf16_f32 v162, v240, v241
	s_waitcnt lgkmcnt(0)
	v_mfma_f32_32x32x16_bf16 v[64:79], v[232:235], v[104:107], v[64:79]
	ds_read_b128 v[228:231], v205 offset:32768
	ds_read_b128 v[232:235], v205 offset:40960
	v_cvt_pk_bf16_f32 v163, v242, v243
	v_cvt_pk_bf16_f32 v164, v244, v245
	v_cvt_pk_bf16_f32 v165, v246, v247
	v_cvt_pk_bf16_f32 v166, v248, v249
	v_cvt_pk_bf16_f32 v167, v250, v251
	v_cvt_pk_bf16_f32 v168, v221, v222
	s_waitcnt lgkmcnt(1)
	v_mfma_f32_32x32x16_bf16 v[80:95], v[228:231], v[100:103], v[80:95]
	v_cvt_pk_bf16_f32 v169, v223, v224
	v_cvt_pk_bf16_f32 v170, v225, v214
	v_cvt_pk_bf16_f32 v171, v215, v216
	v_cvt_pk_bf16_f32 v172, v217, v218
	v_cvt_pk_bf16_f32 v173, v219, v220
	v_cvt_pk_bf16_f32 v174, v252, v226
	s_waitcnt lgkmcnt(0)
	v_mfma_f32_32x32x16_bf16 v[64:79], v[232:235], v[100:103], v[64:79]
	ds_read_b128 v[228:231], v206 offset:32768
	ds_read_b128 v[232:235], v206 offset:40960
	v_cvt_pk_bf16_f32 v175, v227, v253
	v_permlane32_swap_b32_e32 v212, v213
	v_permlane32_swap_b32_e32 v160, v162
	v_permlane32_swap_b32_e32 v161, v163
	v_permlane32_swap_b32_e32 v164, v166
	v_permlane32_swap_b32_e32 v165, v167
	s_waitcnt lgkmcnt(1)
	v_mfma_f32_32x32x16_bf16 v[80:95], v[228:231], v[96:99], v[80:95]
	v_permlane32_swap_b32_e32 v168, v170
	v_permlane32_swap_b32_e32 v169, v171
	v_permlane32_swap_b32_e32 v172, v174
	v_permlane32_swap_b32_e32 v173, v175
	s_waitcnt lgkmcnt(0)
	v_mfma_f32_32x32x16_bf16 v[64:79], v[232:235], v[96:99], v[64:79]
	s_cmpk_gt_u32 s61, 0x80
	s_cselect_b64 s[30:31], -1, 0
	s_and_b64 vcc, exec, s[30:31]
	s_cbranch_vccnz .LBB0_2129
	v_add_co_u32_e32 v132, vcc, 0xfffe8000, v184
	s_nop 1
	v_addc_co_u32_e32 v133, vcc, -1, v185, vcc
	global_load_dwordx4 v[128:131], v[132:133], off
	global_load_dwordx4 v[140:143], v[132:133], off offset:-512
	global_load_dwordx4 v[136:139], v[184:185], off
	s_nop 0
	global_load_dwordx4 v[132:135], v[184:185], off offset:-512
; #define SBAR() __builtin_amdgcn_sched_barrier(0)
; #define SLOAD(i, k0) do { sr_[i].vs0 = *reinterpret_cast<const bf16x8*>(vptr + (size_t)((k0) + sr) * vstr); \
;     sr_[i].vs1 = *reinterpret_cast<const bf16x8*>(vptr + (size_t)((k0) + 32 + sr) * vstr); \
;     sr_[i].ks0 = *reinterpret_cast<const bf16x8*>(kptr + (size_t)((k0) + sr) * kstr); \
;     sr_[i].ks1 = *reinterpret_cast<const bf16x8*>(kptr + (size_t)((k0) + 32 + sr) * kstr); } while (0)
; #define SWRITE(b, i) do { *(LAS bf16x8*)(V_lds + (b) * SHM_V + vst0) = sr_[i].vs0;          \
;     *(LAS bf16x8*)(V_lds + (b) * SHM_V + vst1) = sr_[i].vs1; const int kc = sc * 2;               \
;     *(LAS bf16x8*)(K_lds + (b) * SHM_K + KSWZ(sr, kc)) = sr_[i].ks0;                       \
;     *(LAS bf16x8*)(K_lds + (b) * SHM_K + KSWZ(32 + sr, kc)) = sr_[i].ks1; } while (0)
; #define SWAIT() asm volatile("s_waitcnt vmcnt(4)" ::: "memory")
; template <int NDQ, int NDV> ...
;     ...
;     if (j + 3 < NT) SLOAD(SE, (j + 3) * 64); SBAR();
;     pv_d0<NDV>(o, vb0 + SHM_V, pa0, pa1, pa2, pa3); partialSM(pA0, pA1, m_reg, mnA, alA, Cs, thr);
;     __syncthreads(); SWAIT(); SWRITE(1, SO);
.LBB0_2129:
	s_waitcnt vmcnt(4)
	s_cmp_lg_u64 s[30:31], 0
	s_cbranch_scc0 .Lgqa_nodrain2
	s_waitcnt vmcnt(0)
.Lgqa_nodrain2:
	ds_write_b128 v195, v[148:151] offset:49152
	ds_write_b128 v196, v[152:155] offset:49152
	ds_read_b64_tr_b16 v[214:215], v193 offset:0
	ds_read_b64_tr_b16 v[216:217], v193 offset:0x800
	ds_read_b64_tr_b16 v[218:219], v193 offset:0x1000
	ds_read_b64_tr_b16 v[220:221], v193 offset:0x1800
	ds_read_b64_tr_b16 v[222:223], v193 offset:0x2000
	ds_read_b64_tr_b16 v[224:225], v193 offset:0x2800
	ds_read_b64_tr_b16 v[226:227], v193 offset:0x3000
	ds_read_b64_tr_b16 v[228:229], v193 offset:0x3800
	s_waitcnt lgkmcnt(6)
	v_mfma_f32_32x32x16_bf16 v[0:15], v[160:163], v[214:217], v[0:15]
	ds_read_b64_tr_b16 v[214:215], v193 offset:0x200
	ds_read_b64_tr_b16 v[216:217], v193 offset:0xa00
	v_max_f32_e32 v234, v81, v81
	v_max_f32_e32 v235, v80, v80
	v_max_f32_e32 v234, v235, v234
	v_max3_f32 v234, v234, v82, v83
	v_max3_f32 v234, v234, v84, v85
	v_max3_f32 v234, v234, v86, v87
	s_waitcnt lgkmcnt(6)
	v_mfma_f32_32x32x16_bf16 v[0:15], v[164:167], v[218:221], v[0:15]
	ds_read_b64_tr_b16 v[218:219], v193 offset:0x1200
	ds_read_b64_tr_b16 v[220:221], v193 offset:0x1a00
	v_max3_f32 v234, v234, v88, v89
	v_max3_f32 v234, v234, v90, v91
	v_max3_f32 v234, v234, v92, v93
	v_max3_f32 v234, v234, v94, v95
	v_max3_f32 v234, v234, v64, v65
	v_max3_f32 v234, v234, v66, v67
	s_waitcnt lgkmcnt(6)
	v_mfma_f32_32x32x16_bf16 v[0:15], v[168:171], v[222:225], v[0:15]
	ds_read_b64_tr_b16 v[222:223], v193 offset:0x2200
	ds_read_b64_tr_b16 v[224:225], v193 offset:0x2a00
	ds_read_b64_tr_b16 v[230:231], v193 offset:0x3200
	ds_read_b64_tr_b16 v[232:233], v193 offset:0x3a00
	v_max3_f32 v234, v234, v68, v69
	v_max3_f32 v234, v234, v70, v71
	v_max3_f32 v234, v234, v72, v73
	v_max3_f32 v234, v234, v74, v75
	v_max3_f32 v234, v234, v76, v77
	v_max3_f32 v234, v234, v78, v79
	s_waitcnt lgkmcnt(8)
	v_mfma_f32_32x32x16_bf16 v[0:15], v[172:175], v[226:229], v[0:15]
	v_mov_b32_e32 v235, v234
	s_nop 1
	v_permlane32_swap_b32_e32 v234, v235
	v_max_f32_e32 v235, v235, v235
	v_max_f32_e32 v234, v234, v234
	v_max_f32_e32 v234, v234, v235
	s_waitcnt lgkmcnt(6)
	v_mfma_f32_32x32x16_bf16 v[48:63], v[160:163], v[214:217], v[48:63]
	ds_read_b64_tr_b16 v[214:215], v193 offset:0x400
	ds_read_b64_tr_b16 v[216:217], v193 offset:0xc00
	v_max_f32_e32 v253, v211, v211
	v_sub_f32_e32 v235, v234, v211
	v_max_f32_e32 v234, v253, v234
	v_sub_f32_e32 v253, v211, v234
	v_mul_f32_e32 v253, 0x3e0293ee, v253
	s_waitcnt lgkmcnt(6)
	v_mfma_f32_32x32x16_bf16 v[48:63], v[164:167], v[218:221], v[48:63]
	ds_read_b64_tr_b16 v[218:219], v193 offset:0x1400
	ds_read_b64_tr_b16 v[220:221], v193 offset:0x1c00
	v_exp_f32_e32 v253, v253
	v_cmp_ge_f32_e32 vcc, s48, v235
	s_cmp_eq_u64 vcc, exec
	s_cselect_b64 s[2:3], -1, 0
	v_cndmask_b32_e64 v234, v234, v211, s[2:3]
	s_waitcnt lgkmcnt(6)
	v_mfma_f32_32x32x16_bf16 v[48:63], v[168:171], v[222:225], v[48:63]
	ds_read_b64_tr_b16 v[222:223], v193 offset:0x2400
	ds_read_b64_tr_b16 v[224:225], v193 offset:0x2c00
	ds_read_b64_tr_b16 v[226:227], v193 offset:0x3400
	ds_read_b64_tr_b16 v[228:229], v193 offset:0x3c00
	v_mul_f32_e32 v252, 0xbe0293ee, v234
	v_fmamk_f32 v80, v80, 0x3e0293ee, v252
	v_fmamk_f32 v81, v81, 0x3e0293ee, v252
	v_fmamk_f32 v82, v82, 0x3e0293ee, v252
	v_fmamk_f32 v83, v83, 0x3e0293ee, v252
	v_fmamk_f32 v84, v84, 0x3e0293ee, v252
	s_waitcnt lgkmcnt(8)
	v_mfma_f32_32x32x16_bf16 v[48:63], v[172:175], v[230:233], v[48:63]
	v_fmamk_f32 v85, v85, 0x3e0293ee, v252
	v_fmamk_f32 v86, v86, 0x3e0293ee, v252
	v_fmamk_f32 v87, v87, 0x3e0293ee, v252
	v_fmamk_f32 v88, v88, 0x3e0293ee, v252
	v_fmamk_f32 v89, v89, 0x3e0293ee, v252
	v_fmamk_f32 v90, v90, 0x3e0293ee, v252
	s_waitcnt lgkmcnt(6)
	v_mfma_f32_32x32x16_bf16 v[32:47], v[160:163], v[214:217], v[32:47]
	ds_read_b64_tr_b16 v[214:215], v193 offset:0x600
	ds_read_b64_tr_b16 v[216:217], v193 offset:0xe00
	v_fmamk_f32 v91, v91, 0x3e0293ee, v252
	v_fmamk_f32 v92, v92, 0x3e0293ee, v252
	v_fmamk_f32 v93, v93, 0x3e0293ee, v252
	v_fmamk_f32 v94, v94, 0x3e0293ee, v252
	v_fmamk_f32 v95, v95, 0x3e0293ee, v252
	s_waitcnt lgkmcnt(6)
	v_mfma_f32_32x32x16_bf16 v[32:47], v[164:167], v[218:221], v[32:47]
	ds_read_b64_tr_b16 v[218:219], v193 offset:0x1600
	ds_read_b64_tr_b16 v[220:221], v193 offset:0x1e00
	v_exp_f32_e32 v236, v80
	v_exp_f32_e32 v237, v81
	v_exp_f32_e32 v238, v82
	s_waitcnt lgkmcnt(6)
	v_mfma_f32_32x32x16_bf16 v[32:47], v[168:171], v[222:225], v[32:47]
	ds_read_b64_tr_b16 v[222:223], v193 offset:0x2600
	ds_read_b64_tr_b16 v[224:225], v193 offset:0x2e00
	ds_read_b64_tr_b16 v[230:231], v193 offset:0x3600
	ds_read_b64_tr_b16 v[232:233], v193 offset:0x3e00
	v_exp_f32_e32 v239, v83
	v_exp_f32_e32 v240, v84
	v_exp_f32_e32 v241, v85
	s_waitcnt lgkmcnt(8)
	v_mfma_f32_32x32x16_bf16 v[32:47], v[172:175], v[226:229], v[32:47]
	v_exp_f32_e32 v242, v86
	v_exp_f32_e32 v243, v87
	v_exp_f32_e32 v244, v88
	s_waitcnt lgkmcnt(6)
	v_mfma_f32_32x32x16_bf16 v[16:31], v[160:163], v[214:217], v[16:31]
	v_exp_f32_e32 v245, v89
	v_exp_f32_e32 v246, v90
	v_exp_f32_e32 v247, v91
	s_waitcnt lgkmcnt(4)
	v_mfma_f32_32x32x16_bf16 v[16:31], v[164:167], v[218:221], v[16:31]
	v_exp_f32_e32 v248, v92
	v_exp_f32_e32 v249, v93
	v_exp_f32_e32 v250, v94
	s_waitcnt lgkmcnt(2)
	v_mfma_f32_32x32x16_bf16 v[16:31], v[168:171], v[222:225], v[16:31]
	v_exp_f32_e32 v251, v95
	s_waitcnt lgkmcnt(0)
	v_mfma_f32_32x32x16_bf16 v[16:31], v[172:175], v[230:233], v[16:31]
	s_barrier
	s_waitcnt vmcnt(4)
	s_cmp_lg_u64 s[30:31], 0
	s_cbranch_scc0 .Lgqa_nodrain
	s_waitcnt vmcnt(0)
; #define SWRITE(b, i) do { *(LAS bf16x8*)(V_lds + (b) * SHM_V + vst0) = sr_[i].vs0;          \
;     *(LAS bf16x8*)(V_lds + (b) * SHM_V + vst1) = sr_[i].vs1; const int kc = sc * 2;               \
;     *(LAS bf16x8*)(K_lds + (b) * SHM_K + KSWZ(sr, kc)) = sr_[i].ks0;                       \
;     *(LAS bf16x8*)(K_lds + (b) * SHM_K + KSWZ(32 + sr, kc)) = sr_[i].ks1; } while (0)
; #define SWAIT() asm volatile("s_waitcnt vmcnt(4)" ::: "memory")
; #define RESC(a) do { if (__any((a) < 1.f)) { if (hi == 0) al_l[r32] = (a); asm volatile("s_waitcnt lgkmcnt(0)" ::: "memory"); \
;     _Pragma("unroll") for (int d = 0; d < NDV; ++d) _Pragma("unroll") for (int r = 0; r < 16; ++r) o[d][r] *= al_l[crow(r, hi)]; } } while (0)
; template <int NDQ, int NDV> ...
;     ...
;     __syncthreads(); SWAIT(); SWRITE(1, SO);
;     RESC(alA); __syncthreads();
.Lgqa_nodrain:
	v_cndmask_b32_e64 v161, v253, 1.0, s[2:3]
	v_cmp_gt_f32_e32 vcc, 1.0, v161
	ds_write_b128 v197, v[144:147] offset:16384
	ds_write_b128 v198, v[156:159] offset:16384
	s_cbranch_vccz .LBB0_2133
	s_and_saveexec_b64 s[36:37], s[0:1]
	ds_write_b32 v191, v161 offset:128
	s_or_b64 exec, exec, s[36:37]
	s_waitcnt lgkmcnt(0)
	v_add_u32_e32 v156, v183, v176
	ds_read_b128 v[144:147], v156 offset:224
	ds_read_b128 v[148:151], v156 offset:192
	ds_read_b128 v[152:155], v156 offset:160
	ds_read_b128 v[156:159], v156 offset:128
	s_waitcnt lgkmcnt(3)
	v_pk_mul_f32 v[12:13], v[12:13], v[144:145]
	s_waitcnt lgkmcnt(2)
	v_pk_mul_f32 v[8:9], v[8:9], v[148:149]
	s_waitcnt lgkmcnt(1)
	v_pk_mul_f32 v[4:5], v[4:5], v[152:153]
	v_pk_mul_f32 v[14:15], v[14:15], v[146:147]
	v_pk_mul_f32 v[10:11], v[10:11], v[150:151]
	v_pk_mul_f32 v[6:7], v[6:7], v[154:155]
	s_waitcnt lgkmcnt(0)
	v_pk_mul_f32 v[2:3], v[2:3], v[158:159]
	v_pk_mul_f32 v[0:1], v[0:1], v[156:157]
	v_pk_mul_f32 v[60:61], v[60:61], v[144:145]
	v_pk_mul_f32 v[56:57], v[56:57], v[148:149]
	v_pk_mul_f32 v[52:53], v[52:53], v[152:153]
	v_pk_mul_f32 v[62:63], v[62:63], v[146:147]
	v_pk_mul_f32 v[58:59], v[58:59], v[150:151]
	v_pk_mul_f32 v[54:55], v[54:55], v[154:155]
	v_pk_mul_f32 v[50:51], v[50:51], v[158:159]
	v_pk_mul_f32 v[48:49], v[48:49], v[156:157]
	v_pk_mul_f32 v[44:45], v[44:45], v[144:145]
	v_pk_mul_f32 v[40:41], v[40:41], v[148:149]
	v_pk_mul_f32 v[36:37], v[36:37], v[152:153]
	v_pk_mul_f32 v[46:47], v[46:47], v[146:147]
	v_pk_mul_f32 v[42:43], v[42:43], v[150:151]
	v_pk_mul_f32 v[38:39], v[38:39], v[154:155]
	v_pk_mul_f32 v[34:35], v[34:35], v[158:159]
	v_pk_mul_f32 v[32:33], v[32:33], v[156:157]
	v_pk_mul_f32 v[28:29], v[28:29], v[144:145]
	v_pk_mul_f32 v[24:25], v[24:25], v[148:149]
	v_pk_mul_f32 v[20:21], v[20:21], v[152:153]
	v_pk_mul_f32 v[30:31], v[30:31], v[146:147]
	v_pk_mul_f32 v[26:27], v[26:27], v[150:151]
	v_pk_mul_f32 v[22:23], v[22:23], v[154:155]
	v_pk_mul_f32 v[18:19], v[18:19], v[158:159]
	v_pk_mul_f32 v[16:17], v[16:17], v[156:157]
.LBB0_2133:
	v_mov_b32_e32 v160, v234
	v_pk_fma_f32 v[154:155], v[64:65], s[4:5], v[252:253] op_sel_hi:[1,0,0]
	v_add_f32_e32 v64, v208, v209
	v_fmac_f32_e32 v64, v207, v192
	v_add_f32_e32 v192, v212, v213
	v_pk_fma_f32 v[152:153], v[66:67], s[4:5], v[252:253] op_sel_hi:[1,0,0]
	v_pk_fma_f32 v[148:149], v[68:69], s[4:5], v[252:253] op_sel_hi:[1,0,0]
	v_pk_fma_f32 v[146:147], v[70:71], s[4:5], v[252:253] op_sel_hi:[1,0,0]
	v_pk_fma_f32 v[144:145], v[72:73], s[4:5], v[252:253] op_sel_hi:[1,0,0]
	v_pk_fma_f32 v[158:159], v[74:75], s[4:5], v[252:253] op_sel_hi:[1,0,0]
	v_pk_fma_f32 v[156:157], v[76:77], s[4:5], v[252:253] op_sel_hi:[1,0,0]
	v_pk_fma_f32 v[150:151], v[78:79], s[4:5], v[252:253] op_sel_hi:[1,0,0]
	v_fmac_f32_e32 v192, v64, v210
	v_lshl_add_u64 v[184:185], v[184:185], 0, s[6:7]
	s_and_b64 vcc, exec, s[30:31]
	s_cbranch_vccnz .LBB0_2135
	v_mov_b32_e32 v207, v161
	s_branch .LBB0_2123
